# scale phase: the 16 gain/scale vector loads of a row issued together instead of eight serialized load-wait-store steps
# speedup vs baseline: 1.0152x; 1.0036x over previous
.LBB0_125:
	s_or_b64 exec, exec, s[18:19]
	s_lshr_b32 s2, s2, 12
	s_add_i32 s2, s2, 1
	s_and_b64 s[10:11], s[10:11], exec
	s_cselect_b32 s2, 0, s2
	s_mul_hi_u32 s10, s2, 0x12000
	s_mul_i32 s2, s2, 0x12000
	v_readlane_b32 s18, v243, 42
	v_readlane_b32 s19, v243, 43
	s_add_u32 s2, s18, s2
	s_addc_u32 s11, s19, s10
	s_add_u32 s10, s2, 0x2000
	s_addc_u32 s11, s11, 0
	s_waitcnt lgkmcnt(0)
	global_load_dwordx4 v[100:103], v[34:35], off
	global_load_dwordx4 v[104:107], v52, s[10:11]
	global_load_dwordx4 v[108:111], v[34:35], off offset:1024
	global_load_dwordx4 v[112:115], v53, s[10:11]
	global_load_dwordx4 v[116:119], v[34:35], off offset:2048
	global_load_dwordx4 v[120:123], v54, s[10:11]
	global_load_dwordx4 v[124:127], v[34:35], off offset:3072
	global_load_dwordx4 v[128:131], v55, s[10:11]
	global_load_dwordx4 v[132:135], v[36:37], off
	global_load_dwordx4 v[136:139], v56, s[10:11]
	global_load_dwordx4 v[140:143], v[38:39], off
	global_load_dwordx4 v[144:147], v57, s[10:11]
	global_load_dwordx4 v[148:151], v[40:41], off
	global_load_dwordx4 v[152:155], v58, s[10:11]
	global_load_dwordx4 v[156:159], v[42:43], off
	global_load_dwordx4 v[160:163], v59, s[10:11]
	s_lshl_b64 s[16:17], s[16:17], 12
	v_lshl_add_u64 v[68:69], v[44:45], 0, s[16:17]
	s_waitcnt vmcnt(15)
	v_pk_mul_f32 v[30:31], v[30:31], v[102:103]
	v_pk_mul_f32 v[28:29], v[28:29], v[100:101]
	s_waitcnt vmcnt(14)
	v_pk_add_f32 v[62:63], v[104:105], 1.0 op_sel_hi:[1,0]
	v_pk_add_f32 v[60:61], v[106:107], 1.0 op_sel_hi:[1,0]
	v_pk_mul_f32 v[28:29], v[28:29], v[62:63]
	v_pk_mul_f32 v[30:31], v[30:31], v[60:61]
	v_cvt_pk_bf16_f32 v28, v28, v29
	s_nop 0
	v_cvt_pk_bf16_f32 v29, v30, v31
	global_store_dwordx2 v[68:69], v[28:29], off
	s_waitcnt vmcnt(14)
	v_pk_mul_f32 v[26:27], v[26:27], v[110:111]
	v_pk_mul_f32 v[24:25], v[24:25], v[108:109]
	s_waitcnt vmcnt(13)
	v_pk_add_f32 v[30:31], v[112:113], 1.0 op_sel_hi:[1,0]
	v_pk_add_f32 v[28:29], v[114:115], 1.0 op_sel_hi:[1,0]
	v_pk_mul_f32 v[24:25], v[24:25], v[30:31]
	v_pk_mul_f32 v[26:27], v[26:27], v[28:29]
	v_cvt_pk_bf16_f32 v24, v24, v25
	s_nop 0
	v_cvt_pk_bf16_f32 v25, v26, v27
	global_store_dwordx2 v[68:69], v[24:25], off offset:512
	s_waitcnt vmcnt(13)
	v_pk_mul_f32 v[22:23], v[22:23], v[118:119]
	v_pk_mul_f32 v[20:21], v[20:21], v[116:117]
	s_waitcnt vmcnt(12)
	v_pk_add_f32 v[26:27], v[120:121], 1.0 op_sel_hi:[1,0]
	v_pk_add_f32 v[24:25], v[122:123], 1.0 op_sel_hi:[1,0]
	v_pk_mul_f32 v[20:21], v[20:21], v[26:27]
	v_pk_mul_f32 v[22:23], v[22:23], v[24:25]
	v_cvt_pk_bf16_f32 v20, v20, v21
	s_nop 0
	v_cvt_pk_bf16_f32 v21, v22, v23
	global_store_dwordx2 v[68:69], v[20:21], off offset:1024
	s_waitcnt vmcnt(12)
	v_pk_mul_f32 v[18:19], v[18:19], v[126:127]
	v_pk_mul_f32 v[16:17], v[16:17], v[124:125]
	s_waitcnt vmcnt(11)
	v_pk_add_f32 v[22:23], v[128:129], 1.0 op_sel_hi:[1,0]
	v_pk_add_f32 v[20:21], v[130:131], 1.0 op_sel_hi:[1,0]
	v_pk_mul_f32 v[16:17], v[16:17], v[22:23]
	v_pk_mul_f32 v[18:19], v[18:19], v[20:21]
	v_cvt_pk_bf16_f32 v16, v16, v17
	s_nop 0
	v_cvt_pk_bf16_f32 v17, v18, v19
	global_store_dwordx2 v[68:69], v[16:17], off offset:1536
	s_waitcnt vmcnt(11)
	v_pk_mul_f32 v[14:15], v[14:15], v[134:135]
	v_pk_mul_f32 v[12:13], v[12:13], v[132:133]
	s_waitcnt vmcnt(10)
	v_pk_add_f32 v[18:19], v[136:137], 1.0 op_sel_hi:[1,0]
	v_pk_add_f32 v[16:17], v[138:139], 1.0 op_sel_hi:[1,0]
	v_pk_mul_f32 v[12:13], v[12:13], v[18:19]
	v_pk_mul_f32 v[14:15], v[14:15], v[16:17]
	v_cvt_pk_bf16_f32 v12, v12, v13
	s_nop 0
	v_cvt_pk_bf16_f32 v13, v14, v15
	global_store_dwordx2 v[68:69], v[12:13], off offset:2048
	s_waitcnt vmcnt(10)
	v_pk_mul_f32 v[10:11], v[10:11], v[142:143]
	v_pk_mul_f32 v[8:9], v[8:9], v[140:141]
	s_waitcnt vmcnt(9)
	v_pk_add_f32 v[14:15], v[144:145], 1.0 op_sel_hi:[1,0]
	v_pk_add_f32 v[12:13], v[146:147], 1.0 op_sel_hi:[1,0]
	v_pk_mul_f32 v[8:9], v[8:9], v[14:15]
	v_pk_mul_f32 v[10:11], v[10:11], v[12:13]
	v_cvt_pk_bf16_f32 v8, v8, v9
	s_nop 0
	v_cvt_pk_bf16_f32 v9, v10, v11
	global_store_dwordx2 v[68:69], v[8:9], off offset:2560
	s_waitcnt vmcnt(9)
	v_pk_mul_f32 v[6:7], v[6:7], v[150:151]
	v_pk_mul_f32 v[4:5], v[4:5], v[148:149]
	s_waitcnt vmcnt(8)
	v_pk_add_f32 v[10:11], v[152:153], 1.0 op_sel_hi:[1,0]
	v_pk_add_f32 v[8:9], v[154:155], 1.0 op_sel_hi:[1,0]
	v_pk_mul_f32 v[4:5], v[4:5], v[10:11]
	v_pk_mul_f32 v[6:7], v[6:7], v[8:9]
	v_cvt_pk_bf16_f32 v4, v4, v5
	s_nop 0
	v_cvt_pk_bf16_f32 v5, v6, v7
	global_store_dwordx2 v[68:69], v[4:5], off offset:3072
	v_readlane_b32 s10, v243, 40
	v_readlane_b32 s11, v243, 41
	s_add_u32 s8, s8, s10
	s_addc_u32 s9, s9, s11
	s_add_u32 s4, s4, s6
	s_addc_u32 s5, s5, s7
	s_cmpk_lt_i32 s8, 0x6000
	s_waitcnt vmcnt(8)
	v_pk_mul_f32 v[2:3], v[2:3], v[158:159]
	v_pk_mul_f32 v[0:1], v[0:1], v[156:157]
	s_waitcnt vmcnt(7)
	v_pk_add_f32 v[6:7], v[160:161], 1.0 op_sel_hi:[1,0]
	v_pk_add_f32 v[4:5], v[162:163], 1.0 op_sel_hi:[1,0]
	v_pk_mul_f32 v[0:1], v[0:1], v[6:7]
	v_pk_mul_f32 v[2:3], v[2:3], v[4:5]
	v_cvt_pk_bf16_f32 v0, v0, v1
	s_nop 0
	v_cvt_pk_bf16_f32 v1, v2, v3
	global_store_dwordx2 v[68:69], v[0:1], off offset:3584
	s_cbranch_scc0 .LBB0_132
